# phase 5 first merge GEMM epilogue: all gate loads issued up front
# baseline (speedup 1.0000x reference)
.LBB0_731:
	ds_read_b128 v[150:153], v161
	ds_read_b128 v[164:167], v161 offset:1024
	ds_read_b128 v[168:171], v161 offset:2048
	ds_read_b128 v[172:175], v161 offset:3072
	s_add_u32 s24, s22, 0xfffe0080
	s_addc_u32 s25, s23, -1
	s_cmp_eq_u32 s55, 4
	s_cselect_b32 s27, s15, s25
	s_cselect_b32 s26, s51, s24
	s_cselect_b32 s25, s13, s54
	s_cselect_b32 s24, s52, s53
	v_lshl_add_u64 v[208:209], s[22:23], 0, v[142:143]
	s_add_i32 m0, s21, 0xc000
	ds_read_b128 v[176:179], v162
	ds_read_b128 v[180:183], v162 offset:1024
	ds_read_b128 v[184:187], v162 offset:2048
	ds_read_b128 v[188:191], v162 offset:3072
	ds_read_b128 v[192:195], v162 offset:4096
	ds_read_b128 v[196:199], v162 offset:5120
	ds_read_b128 v[200:203], v162 offset:6144
	ds_read_b128 v[204:207], v162 offset:7168
	global_load_lds_dwordx4 v[208:209], off
	v_lshl_add_u64 v[208:209], s[22:23], 0, v[144:145]
	s_add_i32 m0, s21, 0xe000
	s_nop 0
	global_load_lds_dwordx4 v[208:209], off
	s_waitcnt lgkmcnt(8)
	s_barrier
	s_waitcnt lgkmcnt(0)
	s_setprio 1
	s_waitcnt lgkmcnt(0)
	v_mfma_f32_16x16x32_bf16 v[126:129], v[150:153], v[176:179], v[126:129]
	v_mfma_f32_16x16x32_bf16 v[122:125], v[168:171], v[176:179], v[122:125]
	v_mfma_f32_16x16x32_bf16 v[118:121], v[150:153], v[184:187], v[118:121]
	v_mfma_f32_16x16x32_bf16 v[114:117], v[168:171], v[184:187], v[114:117]
	v_mfma_f32_16x16x32_bf16 v[94:97], v[150:153], v[192:195], v[94:97]
	v_mfma_f32_16x16x32_bf16 v[90:93], v[168:171], v[192:195], v[90:93]
	v_mfma_f32_16x16x32_bf16 v[86:89], v[150:153], v[200:203], v[86:89]
	v_mfma_f32_16x16x32_bf16 v[82:85], v[168:171], v[200:203], v[82:85]
	v_mfma_f32_16x16x32_bf16 v[126:129], v[164:167], v[180:183], v[126:129]
	v_mfma_f32_16x16x32_bf16 v[122:125], v[172:175], v[180:183], v[122:125]
	v_mfma_f32_16x16x32_bf16 v[118:121], v[164:167], v[188:191], v[118:121]
	v_mfma_f32_16x16x32_bf16 v[114:117], v[172:175], v[188:191], v[114:117]
	v_mfma_f32_16x16x32_bf16 v[94:97], v[164:167], v[196:199], v[94:97]
	v_mfma_f32_16x16x32_bf16 v[90:93], v[172:175], v[196:199], v[90:93]
	v_mfma_f32_16x16x32_bf16 v[86:89], v[164:167], v[204:207], v[86:89]
	v_mfma_f32_16x16x32_bf16 v[82:85], v[172:175], v[204:207], v[82:85]
	s_setprio 0
	s_barrier
	s_add_i32 s56, s46, s36
	v_lshl_add_u64 v[224:225], s[24:25], 0, v[132:133]
	s_mov_b32 m0, s56
	ds_read_b128 v[208:211], v163
	ds_read_b128 v[212:215], v163 offset:1024
	ds_read_b128 v[216:219], v163 offset:2048
	ds_read_b128 v[220:223], v163 offset:3072
	global_load_lds_dwordx4 v[224:225], off
	v_lshl_add_u64 v[226:227], s[24:25], 0, v[136:137]
	s_add_i32 m0, s56, 0x2000
	s_nop 0
	global_load_lds_dwordx4 v[226:227], off
	s_barrier
	s_waitcnt lgkmcnt(0)
	s_setprio 1
	s_waitcnt lgkmcnt(0)
	v_mfma_f32_16x16x32_bf16 v[110:113], v[208:211], v[176:179], v[110:113]
	v_mfma_f32_16x16x32_bf16 v[106:109], v[216:219], v[176:179], v[106:109]
	v_mfma_f32_16x16x32_bf16 v[102:105], v[208:211], v[184:187], v[102:105]
	v_mfma_f32_16x16x32_bf16 v[98:101], v[216:219], v[184:187], v[98:101]
	v_mfma_f32_16x16x32_bf16 v[78:81], v[208:211], v[192:195], v[78:81]
	v_mfma_f32_16x16x32_bf16 v[74:77], v[216:219], v[192:195], v[74:77]
	v_mfma_f32_16x16x32_bf16 v[70:73], v[208:211], v[200:203], v[70:73]
	v_mfma_f32_16x16x32_bf16 v[66:69], v[216:219], v[200:203], v[66:69]
	v_mfma_f32_16x16x32_bf16 v[110:113], v[212:215], v[180:183], v[110:113]
	v_mfma_f32_16x16x32_bf16 v[106:109], v[220:223], v[180:183], v[106:109]
	v_mfma_f32_16x16x32_bf16 v[102:105], v[212:215], v[188:191], v[102:105]
	v_mfma_f32_16x16x32_bf16 v[98:101], v[220:223], v[188:191], v[98:101]
	v_mfma_f32_16x16x32_bf16 v[78:81], v[212:215], v[196:199], v[78:81]
	v_mfma_f32_16x16x32_bf16 v[74:77], v[220:223], v[196:199], v[74:77]
	v_mfma_f32_16x16x32_bf16 v[70:73], v[212:215], v[204:207], v[70:73]
	v_mfma_f32_16x16x32_bf16 v[66:69], v[220:223], v[204:207], v[66:69]
	s_setprio 0
	s_mov_b32 m0, s21
	v_lshl_add_u64 v[228:229], s[26:27], 0, v[130:131]
	s_barrier
	ds_read_b128 v[176:179], v162 offset:16384
	ds_read_b128 v[180:183], v162 offset:17408
	ds_read_b128 v[184:187], v162 offset:18432
	ds_read_b128 v[188:191], v162 offset:19456
	ds_read_b128 v[192:195], v162 offset:20480
	ds_read_b128 v[196:199], v162 offset:21504
	ds_read_b128 v[200:203], v162 offset:22528
	ds_read_b128 v[204:207], v162 offset:23552
	global_load_lds_dwordx4 v[228:229], off
	v_lshl_add_u64 v[230:231], s[26:27], 0, v[134:135]
	s_mov_b32 m0, s37
	s_nop 0
	global_load_lds_dwordx4 v[230:231], off
	s_barrier
	s_waitcnt lgkmcnt(0)
	s_setprio 1
	s_waitcnt lgkmcnt(0)
	v_mfma_f32_16x16x32_bf16 v[62:65], v[150:153], v[176:179], v[62:65]
	v_mfma_f32_16x16x32_bf16 v[58:61], v[168:171], v[176:179], v[58:61]
	v_mfma_f32_16x16x32_bf16 v[54:57], v[150:153], v[184:187], v[54:57]
	v_mfma_f32_16x16x32_bf16 v[50:53], v[168:171], v[184:187], v[50:53]
	v_mfma_f32_16x16x32_bf16 v[30:33], v[150:153], v[192:195], v[30:33]
	v_mfma_f32_16x16x32_bf16 v[26:29], v[168:171], v[192:195], v[26:29]
	v_mfma_f32_16x16x32_bf16 v[22:25], v[150:153], v[200:203], v[22:25]
	v_mfma_f32_16x16x32_bf16 v[18:21], v[168:171], v[200:203], v[18:21]
	v_mfma_f32_16x16x32_bf16 v[62:65], v[164:167], v[180:183], v[62:65]
	v_mfma_f32_16x16x32_bf16 v[58:61], v[172:175], v[180:183], v[58:61]
	v_mfma_f32_16x16x32_bf16 v[54:57], v[164:167], v[188:191], v[54:57]
	v_mfma_f32_16x16x32_bf16 v[50:53], v[172:175], v[188:191], v[50:53]
	v_mfma_f32_16x16x32_bf16 v[30:33], v[164:167], v[196:199], v[30:33]
	v_mfma_f32_16x16x32_bf16 v[26:29], v[172:175], v[196:199], v[26:29]
	v_mfma_f32_16x16x32_bf16 v[22:25], v[164:167], v[204:207], v[22:25]
	v_mfma_f32_16x16x32_bf16 v[18:21], v[172:175], v[204:207], v[18:21]
	s_setprio 0
	s_barrier
	s_add_u32 s56, s24, 0x20000
	s_addc_u32 s57, s25, 0
	s_add_i32 s66, s47, s36
	v_lshl_add_u64 v[150:151], s[56:57], 0, v[132:133]
	s_mov_b32 m0, s66
	s_nop 0
	global_load_lds_dwordx4 v[150:151], off
	v_lshl_add_u64 v[150:151], s[56:57], 0, v[136:137]
	s_add_i32 m0, s66, 0x2000
	s_nop 0
	global_load_lds_dwordx4 v[150:151], off
	s_waitcnt vmcnt(6)
	s_barrier
	s_setprio 1
	v_mfma_f32_16x16x32_bf16 v[46:49], v[208:211], v[176:179], v[46:49]
	v_mfma_f32_16x16x32_bf16 v[42:45], v[216:219], v[176:179], v[42:45]
	v_mfma_f32_16x16x32_bf16 v[38:41], v[208:211], v[184:187], v[38:41]
	v_mfma_f32_16x16x32_bf16 v[34:37], v[216:219], v[184:187], v[34:37]
	v_mfma_f32_16x16x32_bf16 v[14:17], v[208:211], v[192:195], v[14:17]
	v_mfma_f32_16x16x32_bf16 v[10:13], v[216:219], v[192:195], v[10:13]
	v_mfma_f32_16x16x32_bf16 v[6:9], v[208:211], v[200:203], v[6:9]
	v_mfma_f32_16x16x32_bf16 v[2:5], v[216:219], v[200:203], v[2:5]
	v_mfma_f32_16x16x32_bf16 v[46:49], v[212:215], v[180:183], v[46:49]
	v_mfma_f32_16x16x32_bf16 v[42:45], v[220:223], v[180:183], v[42:45]
	v_mfma_f32_16x16x32_bf16 v[38:41], v[212:215], v[188:191], v[38:41]
	v_mfma_f32_16x16x32_bf16 v[34:37], v[220:223], v[188:191], v[34:37]
	v_mfma_f32_16x16x32_bf16 v[14:17], v[212:215], v[196:199], v[14:17]
	v_mfma_f32_16x16x32_bf16 v[10:13], v[220:223], v[196:199], v[10:13]
	v_mfma_f32_16x16x32_bf16 v[6:9], v[212:215], v[204:207], v[6:9]
	v_mfma_f32_16x16x32_bf16 v[2:5], v[220:223], v[204:207], v[2:5]
	s_setprio 0
	s_add_i32 s56, 0, 0x18000
	v_add_u32_e32 v172, s56, v160
	s_barrier
	ds_read_b128 v[150:153], v172
	ds_read_b128 v[164:167], v172 offset:1024
	ds_read_b128 v[168:171], v172 offset:2048
	ds_read_b128 v[172:175], v172 offset:3072
	s_add_u32 s26, s26, 0x20000
	s_addc_u32 s27, s27, 0
	s_mov_b32 m0, s38
	v_lshl_add_u64 v[208:209], s[26:27], 0, v[130:131]
	ds_read_b128 v[176:179], v162 offset:32768
	ds_read_b128 v[180:183], v162 offset:33792
	ds_read_b128 v[184:187], v162 offset:34816
	ds_read_b128 v[188:191], v162 offset:35840
	ds_read_b128 v[192:195], v162 offset:36864
	ds_read_b128 v[196:199], v162 offset:37888
	ds_read_b128 v[200:203], v162 offset:38912
	ds_read_b128 v[204:207], v162 offset:39936
	global_load_lds_dwordx4 v[208:209], off
	v_lshl_add_u64 v[208:209], s[26:27], 0, v[134:135]
	s_mov_b32 m0, s39
	s_nop 0
	global_load_lds_dwordx4 v[208:209], off
	s_waitcnt lgkmcnt(8)
	s_barrier
	s_waitcnt lgkmcnt(0)
	s_setprio 1
	s_waitcnt lgkmcnt(0)
	v_mfma_f32_16x16x32_bf16 v[126:129], v[150:153], v[176:179], v[126:129]
	v_mfma_f32_16x16x32_bf16 v[122:125], v[168:171], v[176:179], v[122:125]
	v_mfma_f32_16x16x32_bf16 v[118:121], v[150:153], v[184:187], v[118:121]
	v_mfma_f32_16x16x32_bf16 v[114:117], v[168:171], v[184:187], v[114:117]
	v_mfma_f32_16x16x32_bf16 v[94:97], v[150:153], v[192:195], v[94:97]
	v_mfma_f32_16x16x32_bf16 v[90:93], v[168:171], v[192:195], v[90:93]
	v_mfma_f32_16x16x32_bf16 v[86:89], v[150:153], v[200:203], v[86:89]
	v_mfma_f32_16x16x32_bf16 v[82:85], v[168:171], v[200:203], v[82:85]
	v_mfma_f32_16x16x32_bf16 v[126:129], v[164:167], v[180:183], v[126:129]
	v_mfma_f32_16x16x32_bf16 v[122:125], v[172:175], v[180:183], v[122:125]
	v_mfma_f32_16x16x32_bf16 v[118:121], v[164:167], v[188:191], v[118:121]
	v_mfma_f32_16x16x32_bf16 v[114:117], v[172:175], v[188:191], v[114:117]
	v_mfma_f32_16x16x32_bf16 v[94:97], v[164:167], v[196:199], v[94:97]
	v_mfma_f32_16x16x32_bf16 v[90:93], v[172:175], v[196:199], v[90:93]
	v_mfma_f32_16x16x32_bf16 v[86:89], v[164:167], v[204:207], v[86:89]
	v_mfma_f32_16x16x32_bf16 v[82:85], v[172:175], v[204:207], v[82:85]
	s_setprio 0
	s_barrier
	s_add_i32 s26, 0, 0x1c000
	s_add_i32 s27, s56, s36
	v_add_u32_e32 v220, s26, v160
	v_lshl_add_u64 v[224:225], v[224:225], 0, s[10:11]
	s_mov_b32 m0, s27
	ds_read_b128 v[208:211], v220
	ds_read_b128 v[212:215], v220 offset:1024
	ds_read_b128 v[216:219], v220 offset:2048
	ds_read_b128 v[220:223], v220 offset:3072
	global_load_lds_dwordx4 v[224:225], off
	v_lshl_add_u64 v[224:225], v[226:227], 0, s[10:11]
	s_add_i32 m0, s27, 0x2000
	s_nop 0
	global_load_lds_dwordx4 v[224:225], off
	s_barrier
	s_waitcnt lgkmcnt(0)
	s_setprio 1
	s_waitcnt lgkmcnt(0)
	v_mfma_f32_16x16x32_bf16 v[110:113], v[208:211], v[176:179], v[110:113]
	v_mfma_f32_16x16x32_bf16 v[106:109], v[216:219], v[176:179], v[106:109]
	v_mfma_f32_16x16x32_bf16 v[102:105], v[208:211], v[184:187], v[102:105]
	v_mfma_f32_16x16x32_bf16 v[98:101], v[216:219], v[184:187], v[98:101]
	v_mfma_f32_16x16x32_bf16 v[78:81], v[208:211], v[192:195], v[78:81]
	v_mfma_f32_16x16x32_bf16 v[74:77], v[216:219], v[192:195], v[74:77]
	v_mfma_f32_16x16x32_bf16 v[70:73], v[208:211], v[200:203], v[70:73]
	v_mfma_f32_16x16x32_bf16 v[66:69], v[216:219], v[200:203], v[66:69]
	v_mfma_f32_16x16x32_bf16 v[110:113], v[212:215], v[180:183], v[110:113]
	v_mfma_f32_16x16x32_bf16 v[106:109], v[220:223], v[180:183], v[106:109]
	v_mfma_f32_16x16x32_bf16 v[102:105], v[212:215], v[188:191], v[102:105]
	v_mfma_f32_16x16x32_bf16 v[98:101], v[220:223], v[188:191], v[98:101]
	v_mfma_f32_16x16x32_bf16 v[78:81], v[212:215], v[196:199], v[78:81]
	v_mfma_f32_16x16x32_bf16 v[74:77], v[220:223], v[196:199], v[74:77]
	v_mfma_f32_16x16x32_bf16 v[70:73], v[212:215], v[204:207], v[70:73]
	v_mfma_f32_16x16x32_bf16 v[66:69], v[220:223], v[204:207], v[66:69]
	s_setprio 0
	s_mov_b32 m0, s41
	v_lshl_add_u64 v[224:225], v[228:229], 0, s[10:11]
	s_barrier
	ds_read_b128 v[176:179], v162 offset:49152
	ds_read_b128 v[180:183], v162 offset:50176
	ds_read_b128 v[184:187], v162 offset:51200
	ds_read_b128 v[188:191], v162 offset:52224
	ds_read_b128 v[192:195], v162 offset:53248
	ds_read_b128 v[196:199], v162 offset:54272
	ds_read_b128 v[200:203], v162 offset:55296
	ds_read_b128 v[204:207], v162 offset:56320
	global_load_lds_dwordx4 v[224:225], off
	v_lshl_add_u64 v[224:225], v[230:231], 0, s[10:11]
	s_mov_b32 m0, s42
	s_nop 0
	global_load_lds_dwordx4 v[224:225], off
	s_barrier
	s_waitcnt lgkmcnt(0)
	s_setprio 1
	s_waitcnt lgkmcnt(0)
	v_mfma_f32_16x16x32_bf16 v[62:65], v[150:153], v[176:179], v[62:65]
	v_mfma_f32_16x16x32_bf16 v[58:61], v[168:171], v[176:179], v[58:61]
	v_mfma_f32_16x16x32_bf16 v[54:57], v[150:153], v[184:187], v[54:57]
	v_mfma_f32_16x16x32_bf16 v[50:53], v[168:171], v[184:187], v[50:53]
	v_mfma_f32_16x16x32_bf16 v[30:33], v[150:153], v[192:195], v[30:33]
	v_mfma_f32_16x16x32_bf16 v[26:29], v[168:171], v[192:195], v[26:29]
	v_mfma_f32_16x16x32_bf16 v[22:25], v[150:153], v[200:203], v[22:25]
	v_mfma_f32_16x16x32_bf16 v[18:21], v[168:171], v[200:203], v[18:21]
	v_mfma_f32_16x16x32_bf16 v[62:65], v[164:167], v[180:183], v[62:65]
	v_mfma_f32_16x16x32_bf16 v[58:61], v[172:175], v[180:183], v[58:61]
	v_mfma_f32_16x16x32_bf16 v[54:57], v[164:167], v[188:191], v[54:57]
	v_mfma_f32_16x16x32_bf16 v[50:53], v[172:175], v[188:191], v[50:53]
	v_mfma_f32_16x16x32_bf16 v[30:33], v[164:167], v[196:199], v[30:33]
	v_mfma_f32_16x16x32_bf16 v[26:29], v[172:175], v[196:199], v[26:29]
	v_mfma_f32_16x16x32_bf16 v[22:25], v[164:167], v[204:207], v[22:25]
	v_mfma_f32_16x16x32_bf16 v[18:21], v[172:175], v[204:207], v[18:21]
	s_setprio 0
	s_barrier
	s_add_u32 s24, s24, 0x20080
	s_addc_u32 s25, s25, 0
	s_add_i32 s26, s26, s36
	v_lshl_add_u64 v[150:151], s[24:25], 0, v[132:133]
	s_mov_b32 m0, s26
	s_nop 0
	global_load_lds_dwordx4 v[150:151], off
	v_lshl_add_u64 v[150:151], s[24:25], 0, v[136:137]
	s_add_i32 m0, s26, 0x2000
	s_nop 0
	global_load_lds_dwordx4 v[150:151], off
	s_waitcnt vmcnt(6)
	s_barrier
	s_setprio 1
	v_mfma_f32_16x16x32_bf16 v[46:49], v[208:211], v[176:179], v[46:49]
	v_mfma_f32_16x16x32_bf16 v[42:45], v[216:219], v[176:179], v[42:45]
	v_mfma_f32_16x16x32_bf16 v[38:41], v[208:211], v[184:187], v[38:41]
	v_mfma_f32_16x16x32_bf16 v[34:37], v[216:219], v[184:187], v[34:37]
	v_mfma_f32_16x16x32_bf16 v[14:17], v[208:211], v[192:195], v[14:17]
	v_mfma_f32_16x16x32_bf16 v[10:13], v[216:219], v[192:195], v[10:13]
	v_mfma_f32_16x16x32_bf16 v[6:9], v[208:211], v[200:203], v[6:9]
	v_mfma_f32_16x16x32_bf16 v[2:5], v[216:219], v[200:203], v[2:5]
	v_mfma_f32_16x16x32_bf16 v[46:49], v[212:215], v[180:183], v[46:49]
	v_mfma_f32_16x16x32_bf16 v[42:45], v[220:223], v[180:183], v[42:45]
	v_mfma_f32_16x16x32_bf16 v[38:41], v[212:215], v[188:191], v[38:41]
	v_mfma_f32_16x16x32_bf16 v[34:37], v[220:223], v[188:191], v[34:37]
	v_mfma_f32_16x16x32_bf16 v[14:17], v[212:215], v[196:199], v[14:17]
	v_mfma_f32_16x16x32_bf16 v[10:13], v[220:223], v[196:199], v[10:13]
	v_mfma_f32_16x16x32_bf16 v[6:9], v[212:215], v[204:207], v[6:9]
	v_mfma_f32_16x16x32_bf16 v[2:5], v[220:223], v[204:207], v[2:5]
	s_setprio 0
	s_add_i32 s55, s55, 2
	s_add_u32 s22, s22, 0x100
	s_addc_u32 s23, s23, 0
	s_add_u32 s53, s53, 0x100
	s_addc_u32 s54, s54, 0
	s_cmp_gt_u32 s55, 5
	s_barrier
	s_cbranch_scc0 .LBB0_731
	s_lshl_b32 s13, s20, 3
	s_add_i32 s22, s13, s50
	s_ashr_i32 s23, s22, 31
	s_lshl_b64 s[24:25], s[22:23], 17
	v_lshl_add_u64 v[150:151], v[138:139], 0, s[24:25]
	s_lshl_b32 s13, s20, 2
	s_sub_i32 s22, s22, s13
	s_ashr_i32 s23, s22, 31
	s_lshl_b64 s[22:23], s[22:23], 17
	v_lshl_add_u64 v[152:153], v[140:141], 0, s[22:23]
	v_add_co_u32_e32 v228, vcc, 0x1000, v150
	s_nop 1
	v_addc_co_u32_e32 v229, vcc, 0, v151, vcc
	v_add_co_u32_e32 v150, vcc, 0x3000, v150
	s_nop 1
	v_addc_co_u32_e32 v151, vcc, 0, v151, vcc
	v_add_co_u32_e32 v230, vcc, 0x1000, v152
	s_nop 1
	v_addc_co_u32_e32 v231, vcc, 0, v153, vcc
	v_add_co_u32_e32 v152, vcc, 0x3000, v152
	s_nop 1
	v_addc_co_u32_e32 v153, vcc, 0, v153, vcc
	global_load_dwordx4 v[164:167], v[228:229], off offset:-4096
	global_load_dwordx4 v[168:171], v[228:229], off offset:-3072
	global_load_dwordx4 v[172:175], v[228:229], off offset:-2048
	global_load_dwordx4 v[176:179], v[228:229], off offset:-1024
	global_load_dwordx4 v[180:183], v[228:229], off
	global_load_dwordx4 v[184:187], v[228:229], off offset:1024
	global_load_dwordx4 v[188:191], v[228:229], off offset:2048
	global_load_dwordx4 v[192:195], v[228:229], off offset:3072
	global_load_dwordx4 v[196:199], v[150:151], off offset:-4096
	global_load_dwordx4 v[200:203], v[150:151], off offset:-3072
	global_load_dwordx4 v[204:207], v[150:151], off offset:-2048
	global_load_dwordx4 v[208:211], v[150:151], off offset:-1024
	global_load_dwordx4 v[212:215], v[150:151], off
	global_load_dwordx4 v[216:219], v[150:151], off offset:1024
	global_load_dwordx4 v[220:223], v[150:151], off offset:2048
	s_waitcnt vmcnt(14)
	v_lshlrev_b32_e32 v224, 16, v164
	v_and_b32_e32 v164, 0xffff0000, v164
	v_lshlrev_b32_e32 v225, 16, v165
	v_and_b32_e32 v165, 0xffff0000, v165
	v_lshlrev_b32_e32 v226, 16, v166
	v_and_b32_e32 v166, 0xffff0000, v166
	v_lshlrev_b32_e32 v227, 16, v167
	v_and_b32_e32 v167, 0xffff0000, v167
	v_mul_f32_e32 v126, v126, v224
	v_mul_f32_e32 v127, v127, v164
	v_mul_f32_e32 v128, v128, v225
	v_mul_f32_e32 v129, v129, v165
	v_mul_f32_e32 v122, v122, v226
	v_mul_f32_e32 v123, v123, v166
	v_mul_f32_e32 v124, v124, v227
	v_mul_f32_e32 v125, v125, v167
	v_cvt_pk_bf16_f32 v126, v126, v127
	v_cvt_pk_bf16_f32 v127, v128, v129
	v_cvt_pk_bf16_f32 v128, v122, v123
	v_cvt_pk_bf16_f32 v129, v124, v125
	global_load_dwordx4 v[164:167], v[150:151], off offset:3072
	global_store_dwordx4 v[230:231], v[126:129], off offset:-4096
	s_waitcnt vmcnt(15)
	v_lshlrev_b32_e32 v224, 16, v168
	v_and_b32_e32 v168, 0xffff0000, v168
	v_lshlrev_b32_e32 v225, 16, v169
	v_and_b32_e32 v169, 0xffff0000, v169
	v_lshlrev_b32_e32 v226, 16, v170
	v_and_b32_e32 v170, 0xffff0000, v170
	v_lshlrev_b32_e32 v227, 16, v171
	v_and_b32_e32 v171, 0xffff0000, v171
	v_mul_f32_e32 v110, v110, v224
	v_mul_f32_e32 v111, v111, v168
	v_mul_f32_e32 v112, v112, v225
	v_mul_f32_e32 v113, v113, v169
	v_mul_f32_e32 v106, v106, v226
	v_mul_f32_e32 v107, v107, v170
	v_mul_f32_e32 v108, v108, v227
	v_mul_f32_e32 v109, v109, v171
	v_cvt_pk_bf16_f32 v110, v110, v111
	v_cvt_pk_bf16_f32 v111, v112, v113
	v_cvt_pk_bf16_f32 v112, v106, v107
	v_cvt_pk_bf16_f32 v113, v108, v109
	global_store_dwordx4 v[230:231], v[110:113], off offset:-3072
	s_waitcnt vmcnt(15)
	v_lshlrev_b32_e32 v224, 16, v172
	v_and_b32_e32 v172, 0xffff0000, v172
	v_lshlrev_b32_e32 v225, 16, v173
	v_and_b32_e32 v173, 0xffff0000, v173
	v_lshlrev_b32_e32 v226, 16, v174
	v_and_b32_e32 v174, 0xffff0000, v174
	v_lshlrev_b32_e32 v227, 16, v175
	v_and_b32_e32 v175, 0xffff0000, v175
	v_mul_f32_e32 v118, v118, v224
	v_mul_f32_e32 v119, v119, v172
	v_mul_f32_e32 v120, v120, v225
	v_mul_f32_e32 v121, v121, v173
	v_mul_f32_e32 v114, v114, v226
	v_mul_f32_e32 v115, v115, v174
	v_mul_f32_e32 v116, v116, v227
	v_mul_f32_e32 v117, v117, v175
	v_cvt_pk_bf16_f32 v118, v118, v119
	v_cvt_pk_bf16_f32 v119, v120, v121
	v_cvt_pk_bf16_f32 v120, v114, v115
	v_cvt_pk_bf16_f32 v121, v116, v117
	global_store_dwordx4 v[230:231], v[118:121], off offset:-2048
	s_waitcnt vmcnt(15)
	v_lshlrev_b32_e32 v224, 16, v176
	v_and_b32_e32 v176, 0xffff0000, v176
	v_lshlrev_b32_e32 v225, 16, v177
	v_and_b32_e32 v177, 0xffff0000, v177
	v_lshlrev_b32_e32 v226, 16, v178
	v_and_b32_e32 v178, 0xffff0000, v178
	v_lshlrev_b32_e32 v227, 16, v179
	v_and_b32_e32 v179, 0xffff0000, v179
	v_mul_f32_e32 v102, v102, v224
	v_mul_f32_e32 v103, v103, v176
	v_mul_f32_e32 v104, v104, v225
	v_mul_f32_e32 v105, v105, v177
	v_mul_f32_e32 v98, v98, v226
	v_mul_f32_e32 v99, v99, v178
	v_mul_f32_e32 v100, v100, v227
	v_mul_f32_e32 v101, v101, v179
	v_cvt_pk_bf16_f32 v102, v102, v103
	v_cvt_pk_bf16_f32 v103, v104, v105
	v_cvt_pk_bf16_f32 v104, v98, v99
	v_cvt_pk_bf16_f32 v105, v100, v101
	global_store_dwordx4 v[230:231], v[102:105], off offset:-1024
	s_waitcnt vmcnt(15)
	v_lshlrev_b32_e32 v224, 16, v180
	v_and_b32_e32 v180, 0xffff0000, v180
	v_lshlrev_b32_e32 v225, 16, v181
	v_and_b32_e32 v181, 0xffff0000, v181
	v_lshlrev_b32_e32 v226, 16, v182
	v_and_b32_e32 v182, 0xffff0000, v182
	v_lshlrev_b32_e32 v227, 16, v183
	v_and_b32_e32 v183, 0xffff0000, v183
	v_mul_f32_e32 v94, v94, v224
	v_mul_f32_e32 v95, v95, v180
	v_mul_f32_e32 v96, v96, v225
	v_mul_f32_e32 v97, v97, v181
	v_mul_f32_e32 v90, v90, v226
	v_mul_f32_e32 v91, v91, v182
	v_mul_f32_e32 v92, v92, v227
	v_mul_f32_e32 v93, v93, v183
	v_cvt_pk_bf16_f32 v94, v94, v95
	v_cvt_pk_bf16_f32 v95, v96, v97
	v_cvt_pk_bf16_f32 v96, v90, v91
	v_cvt_pk_bf16_f32 v97, v92, v93
	global_store_dwordx4 v[230:231], v[94:97], off
	s_waitcnt vmcnt(15)
	v_lshlrev_b32_e32 v224, 16, v184
	v_and_b32_e32 v184, 0xffff0000, v184
	v_lshlrev_b32_e32 v225, 16, v185
	v_and_b32_e32 v185, 0xffff0000, v185
	v_lshlrev_b32_e32 v226, 16, v186
	v_and_b32_e32 v186, 0xffff0000, v186
	v_lshlrev_b32_e32 v227, 16, v187
	v_and_b32_e32 v187, 0xffff0000, v187
	v_mul_f32_e32 v78, v78, v224
	v_mul_f32_e32 v79, v79, v184
	v_mul_f32_e32 v80, v80, v225
	v_mul_f32_e32 v81, v81, v185
	v_mul_f32_e32 v74, v74, v226
	v_mul_f32_e32 v75, v75, v186
	v_mul_f32_e32 v76, v76, v227
	v_mul_f32_e32 v77, v77, v187
	v_cvt_pk_bf16_f32 v78, v78, v79
	v_cvt_pk_bf16_f32 v79, v80, v81
	v_cvt_pk_bf16_f32 v80, v74, v75
	v_cvt_pk_bf16_f32 v81, v76, v77
	global_store_dwordx4 v[230:231], v[78:81], off offset:1024
	s_waitcnt vmcnt(15)
	v_lshlrev_b32_e32 v224, 16, v188
	v_and_b32_e32 v188, 0xffff0000, v188
	v_lshlrev_b32_e32 v225, 16, v189
	v_and_b32_e32 v189, 0xffff0000, v189
	v_lshlrev_b32_e32 v226, 16, v190
	v_and_b32_e32 v190, 0xffff0000, v190
	v_lshlrev_b32_e32 v227, 16, v191
	v_and_b32_e32 v191, 0xffff0000, v191
	v_mul_f32_e32 v86, v86, v224
	v_mul_f32_e32 v87, v87, v188
	v_mul_f32_e32 v88, v88, v225
	v_mul_f32_e32 v89, v89, v189
	v_mul_f32_e32 v82, v82, v226
	v_mul_f32_e32 v83, v83, v190
	v_mul_f32_e32 v84, v84, v227
	v_mul_f32_e32 v85, v85, v191
	v_cvt_pk_bf16_f32 v86, v86, v87
	v_cvt_pk_bf16_f32 v87, v88, v89
	v_cvt_pk_bf16_f32 v88, v82, v83
	v_cvt_pk_bf16_f32 v89, v84, v85
	global_store_dwordx4 v[230:231], v[86:89], off offset:2048
	s_waitcnt vmcnt(15)
	v_lshlrev_b32_e32 v224, 16, v192
	v_and_b32_e32 v192, 0xffff0000, v192
	v_lshlrev_b32_e32 v225, 16, v193
	v_and_b32_e32 v193, 0xffff0000, v193
	v_lshlrev_b32_e32 v226, 16, v194
	v_and_b32_e32 v194, 0xffff0000, v194
	v_lshlrev_b32_e32 v227, 16, v195
	v_and_b32_e32 v195, 0xffff0000, v195
	v_mul_f32_e32 v70, v70, v224
	v_mul_f32_e32 v71, v71, v192
	v_mul_f32_e32 v72, v72, v225
	v_mul_f32_e32 v73, v73, v193
	v_mul_f32_e32 v66, v66, v226
	v_mul_f32_e32 v67, v67, v194
	v_mul_f32_e32 v68, v68, v227
	v_mul_f32_e32 v69, v69, v195
	v_cvt_pk_bf16_f32 v70, v70, v71
	v_cvt_pk_bf16_f32 v71, v72, v73
	v_cvt_pk_bf16_f32 v72, v66, v67
	v_cvt_pk_bf16_f32 v73, v68, v69
	global_store_dwordx4 v[230:231], v[70:73], off offset:3072
	s_waitcnt vmcnt(15)
	v_lshlrev_b32_e32 v224, 16, v196
	v_and_b32_e32 v196, 0xffff0000, v196
	v_lshlrev_b32_e32 v225, 16, v197
	v_and_b32_e32 v197, 0xffff0000, v197
	v_lshlrev_b32_e32 v226, 16, v198
	v_and_b32_e32 v198, 0xffff0000, v198
	v_lshlrev_b32_e32 v227, 16, v199
	v_and_b32_e32 v199, 0xffff0000, v199
	v_mul_f32_e32 v62, v62, v224
	v_mul_f32_e32 v63, v63, v196
	v_mul_f32_e32 v64, v64, v225
	v_mul_f32_e32 v65, v65, v197
	v_mul_f32_e32 v58, v58, v226
	v_mul_f32_e32 v59, v59, v198
	v_mul_f32_e32 v60, v60, v227
	v_mul_f32_e32 v61, v61, v199
	v_cvt_pk_bf16_f32 v62, v62, v63
	v_cvt_pk_bf16_f32 v63, v64, v65
	v_cvt_pk_bf16_f32 v64, v58, v59
	v_cvt_pk_bf16_f32 v65, v60, v61
	global_store_dwordx4 v[152:153], v[62:65], off offset:-4096
	s_waitcnt vmcnt(15)
	v_lshlrev_b32_e32 v224, 16, v200
	v_and_b32_e32 v200, 0xffff0000, v200
	v_lshlrev_b32_e32 v225, 16, v201
	v_and_b32_e32 v201, 0xffff0000, v201
	v_lshlrev_b32_e32 v226, 16, v202
	v_and_b32_e32 v202, 0xffff0000, v202
	v_lshlrev_b32_e32 v227, 16, v203
	v_and_b32_e32 v203, 0xffff0000, v203
	v_mul_f32_e32 v46, v46, v224
	v_mul_f32_e32 v47, v47, v200
	v_mul_f32_e32 v48, v48, v225
	v_mul_f32_e32 v49, v49, v201
	v_mul_f32_e32 v42, v42, v226
	v_mul_f32_e32 v43, v43, v202
	v_mul_f32_e32 v44, v44, v227
	v_mul_f32_e32 v45, v45, v203
	v_cvt_pk_bf16_f32 v46, v46, v47
	v_cvt_pk_bf16_f32 v47, v48, v49
	v_cvt_pk_bf16_f32 v48, v42, v43
	v_cvt_pk_bf16_f32 v49, v44, v45
	global_store_dwordx4 v[152:153], v[46:49], off offset:-3072
	s_waitcnt vmcnt(15)
	v_lshlrev_b32_e32 v224, 16, v204
	v_and_b32_e32 v204, 0xffff0000, v204
	v_lshlrev_b32_e32 v225, 16, v205
	v_and_b32_e32 v205, 0xffff0000, v205
	v_lshlrev_b32_e32 v226, 16, v206
	v_and_b32_e32 v206, 0xffff0000, v206
	v_lshlrev_b32_e32 v227, 16, v207
	v_and_b32_e32 v207, 0xffff0000, v207
	v_mul_f32_e32 v54, v54, v224
	v_mul_f32_e32 v55, v55, v204
	v_mul_f32_e32 v56, v56, v225
	v_mul_f32_e32 v57, v57, v205
	v_mul_f32_e32 v50, v50, v226
	v_mul_f32_e32 v51, v51, v206
	v_mul_f32_e32 v52, v52, v227
	v_mul_f32_e32 v53, v53, v207
	v_cvt_pk_bf16_f32 v54, v54, v55
	v_cvt_pk_bf16_f32 v55, v56, v57
	v_cvt_pk_bf16_f32 v56, v50, v51
	v_cvt_pk_bf16_f32 v57, v52, v53
	global_store_dwordx4 v[152:153], v[54:57], off offset:-2048
	s_waitcnt vmcnt(15)
	v_lshlrev_b32_e32 v224, 16, v208
	v_and_b32_e32 v208, 0xffff0000, v208
	v_lshlrev_b32_e32 v225, 16, v209
	v_and_b32_e32 v209, 0xffff0000, v209
	v_lshlrev_b32_e32 v226, 16, v210
	v_and_b32_e32 v210, 0xffff0000, v210
	v_lshlrev_b32_e32 v227, 16, v211
	v_and_b32_e32 v211, 0xffff0000, v211
	v_mul_f32_e32 v38, v38, v224
	v_mul_f32_e32 v39, v39, v208
	v_mul_f32_e32 v40, v40, v225
	v_mul_f32_e32 v41, v41, v209
	v_mul_f32_e32 v34, v34, v226
	v_mul_f32_e32 v35, v35, v210
	v_mul_f32_e32 v36, v36, v227
	v_mul_f32_e32 v37, v37, v211
	v_cvt_pk_bf16_f32 v38, v38, v39
	v_cvt_pk_bf16_f32 v39, v40, v41
	v_cvt_pk_bf16_f32 v40, v34, v35
	v_cvt_pk_bf16_f32 v41, v36, v37
	global_store_dwordx4 v[152:153], v[38:41], off offset:-1024
	s_waitcnt vmcnt(15)
	v_lshlrev_b32_e32 v224, 16, v212
	v_and_b32_e32 v212, 0xffff0000, v212
	v_lshlrev_b32_e32 v225, 16, v213
	v_and_b32_e32 v213, 0xffff0000, v213
	v_lshlrev_b32_e32 v226, 16, v214
	v_and_b32_e32 v214, 0xffff0000, v214
	v_lshlrev_b32_e32 v227, 16, v215
	v_and_b32_e32 v215, 0xffff0000, v215
	v_mul_f32_e32 v30, v30, v224
	v_mul_f32_e32 v31, v31, v212
	v_mul_f32_e32 v32, v32, v225
	v_mul_f32_e32 v33, v33, v213
	v_mul_f32_e32 v26, v26, v226
	v_mul_f32_e32 v27, v27, v214
	v_mul_f32_e32 v28, v28, v227
	v_mul_f32_e32 v29, v29, v215
	v_cvt_pk_bf16_f32 v30, v30, v31
	v_cvt_pk_bf16_f32 v31, v32, v33
	v_cvt_pk_bf16_f32 v32, v26, v27
	v_cvt_pk_bf16_f32 v33, v28, v29
	global_store_dwordx4 v[152:153], v[30:33], off
	s_waitcnt vmcnt(15)
	v_lshlrev_b32_e32 v224, 16, v216
	v_and_b32_e32 v216, 0xffff0000, v216
	v_lshlrev_b32_e32 v225, 16, v217
	v_and_b32_e32 v217, 0xffff0000, v217
	v_lshlrev_b32_e32 v226, 16, v218
	v_and_b32_e32 v218, 0xffff0000, v218
	v_lshlrev_b32_e32 v227, 16, v219
	v_and_b32_e32 v219, 0xffff0000, v219
	v_mul_f32_e32 v14, v14, v224
	v_mul_f32_e32 v15, v15, v216
	v_mul_f32_e32 v16, v16, v225
	v_mul_f32_e32 v17, v17, v217
	v_mul_f32_e32 v10, v10, v226
	v_mul_f32_e32 v11, v11, v218
	v_mul_f32_e32 v12, v12, v227
	v_mul_f32_e32 v13, v13, v219
	v_cvt_pk_bf16_f32 v14, v14, v15
	v_cvt_pk_bf16_f32 v15, v16, v17
	v_cvt_pk_bf16_f32 v16, v10, v11
	v_cvt_pk_bf16_f32 v17, v12, v13
	global_store_dwordx4 v[152:153], v[14:17], off offset:1024
	s_waitcnt vmcnt(15)
	v_lshlrev_b32_e32 v224, 16, v220
	v_and_b32_e32 v220, 0xffff0000, v220
	v_lshlrev_b32_e32 v225, 16, v221
	v_and_b32_e32 v221, 0xffff0000, v221
	v_lshlrev_b32_e32 v226, 16, v222
	v_and_b32_e32 v222, 0xffff0000, v222
	v_lshlrev_b32_e32 v227, 16, v223
	v_and_b32_e32 v223, 0xffff0000, v223
	v_mul_f32_e32 v22, v22, v224
	v_mul_f32_e32 v23, v23, v220
	v_mul_f32_e32 v24, v24, v225
	v_mul_f32_e32 v25, v25, v221
	v_mul_f32_e32 v18, v18, v226
	v_mul_f32_e32 v19, v19, v222
	v_mul_f32_e32 v20, v20, v227
	v_mul_f32_e32 v21, v21, v223
	v_cvt_pk_bf16_f32 v22, v22, v23
	v_cvt_pk_bf16_f32 v23, v24, v25
	v_cvt_pk_bf16_f32 v24, v18, v19
	v_cvt_pk_bf16_f32 v25, v20, v21
	global_store_dwordx4 v[152:153], v[22:25], off offset:2048
	s_waitcnt vmcnt(15)
	v_lshlrev_b32_e32 v224, 16, v164
	v_and_b32_e32 v164, 0xffff0000, v164
	v_lshlrev_b32_e32 v225, 16, v165
	v_and_b32_e32 v165, 0xffff0000, v165
	v_lshlrev_b32_e32 v226, 16, v166
	v_and_b32_e32 v166, 0xffff0000, v166
	v_lshlrev_b32_e32 v227, 16, v167
	v_and_b32_e32 v167, 0xffff0000, v167
	v_mul_f32_e32 v6, v6, v224
	v_mul_f32_e32 v7, v7, v164
	v_mul_f32_e32 v8, v8, v225
	v_mul_f32_e32 v9, v9, v165
	v_mul_f32_e32 v2, v2, v226
	v_mul_f32_e32 v3, v3, v166
	v_mul_f32_e32 v4, v4, v227
	v_mul_f32_e32 v5, v5, v167
	v_cvt_pk_bf16_f32 v6, v6, v7
	v_cvt_pk_bf16_f32 v7, v8, v9
	v_cvt_pk_bf16_f32 v8, v2, v3
	v_cvt_pk_bf16_f32 v9, v4, v5
	global_store_dwordx4 v[152:153], v[6:9], off offset:3072
	s_and_b64 vcc, exec, s[2:3]
	s_mov_b32 s50, s12
	s_mov_b32 s20, s14
	s_mov_b64 s[24:25], s[18:19]
	s_mov_b64 s[22:23], s[16:17]
	s_cbranch_vccz .LBB0_724
	s_waitcnt vmcnt(0)
	s_cmpk_gt_u32 s28, 0xff
	s_cbranch_scc1 .LBB0_735
	s_barrier
